# NSA tile loops: probabilities in place, score-max as 16 packed-f32 subtractions instead of 32 scalar ones; same MFMA and LDS order
# speedup vs baseline: 1.0100x; 1.0013x over previous
; #define LAS __attribute__((address_space(3)))
; __device__ __forceinline__ unsigned cvtpk(float lo, float hi) { f32x2v_ v = {lo, hi}; bf16x2v_ b = __builtin_convertvector(v, bf16x2v_); return __builtin_bit_cast(unsigned, b); }
; __device__ __forceinline__ void nsa_pv(f32x16& o0, f32x16& o1, const f32x16& p0, const f32x16& p1, const LAS unsigned char* vslot, int lane, int hi) {
;     u32x4 pw[4];
; #pragma unroll
;     for (int k = 0; k < 4; ++k) { pw[0][k] = cvtpk(p0[2 * k], p0[2 * k + 1]); pw[1][k] = cvtpk(p0[8 + 2 * k], p0[9 + 2 * k]); pw[2][k] = cvtpk(p1[2 * k], p1[2 * k + 1]); pw[3][k] = cvtpk(p1[8 + 2 * k], p1[9 + 2 * k]); }
;     const LAS unsigned char* vp = vslot + ((lane >> 4) & 1) * 32 + (lane & 3) * 8 + (4 * hi + ((lane & 15) >> 2)) * 64;
; #pragma unroll
;     for (int ks = 0; ks < 4; ++ks) {
;         const s16x4v a0 = __builtin_bit_cast(s16x4v, __builtin_amdgcn_ds_read_tr16_b64_v4i16((LAS s16x4v*)(vp + ks * 1024)));
;         const s16x4v a1 = __builtin_bit_cast(s16x4v, __builtin_amdgcn_ds_read_tr16_b64_v4i16((LAS s16x4v*)(vp + ks * 1024 + 512)));
;         const s16x4v b0 = __builtin_bit_cast(s16x4v, __builtin_amdgcn_ds_read_tr16_b64_v4i16((LAS s16x4v*)(vp + 4096 + ks * 1024)));
;         const s16x4v b1 = __builtin_bit_cast(s16x4v, __builtin_amdgcn_ds_read_tr16_b64_v4i16((LAS s16x4v*)(vp + 4096 + ks * 1024 + 512)));
;         const bf16x8v va = {a0[0], a0[1], a0[2], a0[3], a1[0], a1[1], a1[2], a1[3]}, vb = {b0[0], b0[1], b0[2], b0[3], b1[0], b1[1], b1[2], b1[3]};
;         const bf16x8v pa = __builtin_bit_cast(bf16x8v, pw[ks]);
;         o0 = __builtin_amdgcn_mfma_f32_32x32x16_bf16(pa, va, o0, 0, 0, 0); o1 = __builtin_amdgcn_mfma_f32_32x32x16_bf16(pa, vb, o1, 0, 0, 0); }
; }
; __device__ __forceinline__ void nsa_softmax_pv(NsaSm& st, f32x16& p0, f32x16& p1, const LAS unsigned char* vslot, LAS float* wsf, int lane, int r32, int hi, bool on = true) {
;     const float rmx = rowmax32(p0, p1); const float rm = on ? rmx : SNEG; const float mn = fmaxf(st.m, rm); const float f = __builtin_amdgcn_exp2f(st.m - mn); st.m = mn;
;     const float cs = on ? mn : 1.0e30f;
;     float s = 0.f;
; #pragma unroll
;     for (int r = 0; r < 16; ++r) { p0[r] = __builtin_amdgcn_exp2f(p0[r] - cs); p1[r] = __builtin_amdgcn_exp2f(p1[r] - cs); s += p0[r] + p1[r]; }
;     st.l = st.l * f + s;
.LBB0_1333:
	v_mov_b32_e32 v2, 0x7149f2ca
	v_cndmask_b32_e64 v2, v2, v0, s[16:17]
	v_pk_add_f32 v[80:81], v[80:81], v[2:3] op_sel_hi:[1,0] neg_lo:[0,1] neg_hi:[0,1]
	v_pk_add_f32 v[82:83], v[82:83], v[2:3] op_sel_hi:[1,0] neg_lo:[0,1] neg_hi:[0,1]
	v_pk_add_f32 v[84:85], v[84:85], v[2:3] op_sel_hi:[1,0] neg_lo:[0,1] neg_hi:[0,1]
	v_pk_add_f32 v[86:87], v[86:87], v[2:3] op_sel_hi:[1,0] neg_lo:[0,1] neg_hi:[0,1]
	v_pk_add_f32 v[88:89], v[88:89], v[2:3] op_sel_hi:[1,0] neg_lo:[0,1] neg_hi:[0,1]
	v_pk_add_f32 v[90:91], v[90:91], v[2:3] op_sel_hi:[1,0] neg_lo:[0,1] neg_hi:[0,1]
	v_pk_add_f32 v[92:93], v[92:93], v[2:3] op_sel_hi:[1,0] neg_lo:[0,1] neg_hi:[0,1]
	v_pk_add_f32 v[94:95], v[94:95], v[2:3] op_sel_hi:[1,0] neg_lo:[0,1] neg_hi:[0,1]
	v_pk_add_f32 v[128:129], v[128:129], v[2:3] op_sel_hi:[1,0] neg_lo:[0,1] neg_hi:[0,1]
	v_pk_add_f32 v[130:131], v[130:131], v[2:3] op_sel_hi:[1,0] neg_lo:[0,1] neg_hi:[0,1]
	v_pk_add_f32 v[132:133], v[132:133], v[2:3] op_sel_hi:[1,0] neg_lo:[0,1] neg_hi:[0,1]
	v_pk_add_f32 v[134:135], v[134:135], v[2:3] op_sel_hi:[1,0] neg_lo:[0,1] neg_hi:[0,1]
	v_pk_add_f32 v[136:137], v[136:137], v[2:3] op_sel_hi:[1,0] neg_lo:[0,1] neg_hi:[0,1]
	v_pk_add_f32 v[138:139], v[138:139], v[2:3] op_sel_hi:[1,0] neg_lo:[0,1] neg_hi:[0,1]
	v_pk_add_f32 v[140:141], v[140:141], v[2:3] op_sel_hi:[1,0] neg_lo:[0,1] neg_hi:[0,1]
	v_pk_add_f32 v[142:143], v[142:143], v[2:3] op_sel_hi:[1,0] neg_lo:[0,1] neg_hi:[0,1]
	v_exp_f32_e32 v80, v80
	v_exp_f32_e32 v81, v81
	v_exp_f32_e32 v82, v82
	v_exp_f32_e32 v83, v83
	v_exp_f32_e32 v84, v84
	v_exp_f32_e32 v85, v85
	v_exp_f32_e32 v86, v86
	v_exp_f32_e32 v87, v87
	v_add_u32_e32 v103, s20, v238
	v_cvt_pk_bf16_f32 v104, v80, v81
	v_cvt_pk_bf16_f32 v105, v82, v83
	v_cvt_pk_bf16_f32 v106, v84, v85
	v_cvt_pk_bf16_f32 v107, v86, v87
	ds_read_b64_tr_b16 v[116:117], v103 offset:17408
	ds_read_b64_tr_b16 v[118:119], v103 offset:17920
	ds_read_b64_tr_b16 v[120:121], v103 offset:21504
	ds_read_b64_tr_b16 v[122:123], v103 offset:22016
	v_exp_f32_e32 v88, v88
	v_exp_f32_e32 v89, v89
	v_exp_f32_e32 v90, v90
	v_exp_f32_e32 v91, v91
	v_exp_f32_e32 v92, v92
	v_exp_f32_e32 v93, v93
	v_exp_f32_e32 v94, v94
	v_exp_f32_e32 v95, v95
	v_exp_f32_e32 v128, v128
	v_exp_f32_e32 v129, v129
	v_exp_f32_e32 v130, v130
	v_exp_f32_e32 v131, v131
	v_exp_f32_e32 v132, v132
	v_exp_f32_e32 v133, v133
	v_exp_f32_e32 v134, v134
	v_exp_f32_e32 v135, v135
	s_waitcnt lgkmcnt(2)
	v_mfma_f32_32x32x16_bf16 v[64:79], v[104:107], v[116:119], v[64:79]
	v_cvt_pk_bf16_f32 v108, v88, v89
	v_cvt_pk_bf16_f32 v109, v90, v91
	v_cvt_pk_bf16_f32 v110, v92, v93
	v_cvt_pk_bf16_f32 v111, v94, v95
	v_cvt_pk_bf16_f32 v112, v128, v129
	v_cvt_pk_bf16_f32 v113, v130, v131
	v_cvt_pk_bf16_f32 v114, v132, v133
	s_waitcnt lgkmcnt(0)
	v_mfma_f32_32x32x16_bf16 v[48:63], v[104:107], v[120:123], v[48:63]
	ds_read_b64_tr_b16 v[104:105], v103 offset:18432
	ds_read_b64_tr_b16 v[106:107], v103 offset:18944
	ds_read_b64_tr_b16 v[116:117], v103 offset:22528
	ds_read_b64_tr_b16 v[118:119], v103 offset:23040
	v_cvt_pk_bf16_f32 v115, v134, v135
	v_exp_f32_e32 v136, v136
	v_exp_f32_e32 v137, v137
	v_exp_f32_e32 v138, v138
	v_exp_f32_e32 v139, v139
	v_exp_f32_e32 v140, v140
	v_exp_f32_e32 v141, v141
	v_exp_f32_e32 v142, v142
	v_exp_f32_e32 v143, v143
	v_cvt_pk_bf16_f32 v2, v136, v137
	v_cvt_pk_bf16_f32 v3, v138, v139
	v_cvt_pk_bf16_f32 v4, v140, v141
	s_waitcnt lgkmcnt(2)
	v_mfma_f32_32x32x16_bf16 v[64:79], v[108:111], v[104:107], v[64:79]
	v_cvt_pk_bf16_f32 v5, v142, v143
	s_andn2_b64 vcc, exec, s[36:37]
	s_waitcnt lgkmcnt(0)
	v_mfma_f32_32x32x16_bf16 v[48:63], v[108:111], v[116:119], v[48:63]
	ds_read_b64_tr_b16 v[104:105], v103 offset:19456
	ds_read_b64_tr_b16 v[106:107], v103 offset:19968
	ds_read_b64_tr_b16 v[108:109], v103 offset:23552
	ds_read_b64_tr_b16 v[110:111], v103 offset:24064
	s_waitcnt lgkmcnt(2)
	v_mfma_f32_32x32x16_bf16 v[64:79], v[112:115], v[104:107], v[64:79]
	s_waitcnt lgkmcnt(0)
	v_mfma_f32_32x32x16_bf16 v[48:63], v[112:115], v[108:111], v[48:63]
	ds_read_b64_tr_b16 v[104:105], v103 offset:20480
	ds_read_b64_tr_b16 v[106:107], v103 offset:20992
	ds_read_b64_tr_b16 v[108:109], v103 offset:24576
	ds_read_b64_tr_b16 v[110:111], v103 offset:25088
	s_waitcnt lgkmcnt(2)
	v_mfma_f32_32x32x16_bf16 v[64:79], v[2:5], v[104:107], v[64:79]
	s_waitcnt lgkmcnt(0)
	v_mfma_f32_32x32x16_bf16 v[48:63], v[2:5], v[108:111], v[48:63]
	s_cbranch_vccnz .LBB0_1335
	s_xor_b32 s2, s20, 0x2000
	v_add_u32_e32 v2, s2, v251
	s_waitcnt vmcnt(1)
	ds_write_b128 v2, v[144:147] offset:1024
	s_waitcnt vmcnt(0)
	ds_write_b128 v2, v[148:151] offset:17408
.LBB0_1335:
	v_pk_add_f32 v[80:81], v[80:81], v[82:83]
	v_pk_add_f32 v[84:85], v[84:85], v[86:87]
	v_pk_add_f32 v[88:89], v[88:89], v[90:91]
	v_pk_add_f32 v[92:93], v[92:93], v[94:95]
	v_pk_add_f32 v[128:129], v[128:129], v[130:131]
	v_pk_add_f32 v[132:133], v[132:133], v[134:135]
	v_pk_add_f32 v[136:137], v[136:137], v[138:139]
	v_pk_add_f32 v[140:141], v[140:141], v[142:143]
	v_pk_add_f32 v[80:81], v[80:81], v[84:85]
	v_pk_add_f32 v[88:89], v[88:89], v[92:93]
	v_pk_add_f32 v[128:129], v[128:129], v[132:133]
	v_pk_add_f32 v[136:137], v[136:137], v[140:141]
	v_pk_add_f32 v[80:81], v[80:81], v[88:89]
	v_pk_add_f32 v[128:129], v[128:129], v[136:137]
	v_pk_add_f32 v[80:81], v[80:81], v[128:129]
	v_add_f32_e32 v2, v80, v81
	v_fmac_f32_e32 v2, v157, v6
	s_andn2_b64 vcc, exec, s[6:7]
	s_xor_b32 s42, s42, 1
	s_waitcnt lgkmcnt(0)
	s_barrier
	s_cbranch_vccz .LBB0_1337
	v_mov_b32_e32 v157, v2
	v_mov_b32_e32 v158, v0
	s_mov_b32 s8, s43
	s_mov_b64 s[2:3], s[4:5]
	s_branch .LBB0_1323

; #define LAS __attribute__((address_space(3)))
; __device__ __forceinline__ unsigned cvtpk(float lo, float hi) { f32x2v_ v = {lo, hi}; bf16x2v_ b = __builtin_convertvector(v, bf16x2v_); return __builtin_bit_cast(unsigned, b); }
; __device__ __forceinline__ void nsa_pv(f32x16& o0, f32x16& o1, const f32x16& p0, const f32x16& p1, const LAS unsigned char* vslot, int lane, int hi) {
;     u32x4 pw[4];
; #pragma unroll
;     for (int k = 0; k < 4; ++k) { pw[0][k] = cvtpk(p0[2 * k], p0[2 * k + 1]); pw[1][k] = cvtpk(p0[8 + 2 * k], p0[9 + 2 * k]); pw[2][k] = cvtpk(p1[2 * k], p1[2 * k + 1]); pw[3][k] = cvtpk(p1[8 + 2 * k], p1[9 + 2 * k]); }
;     const LAS unsigned char* vp = vslot + ((lane >> 4) & 1) * 32 + (lane & 3) * 8 + (4 * hi + ((lane & 15) >> 2)) * 64;
; #pragma unroll
;     for (int ks = 0; ks < 4; ++ks) {
;         const s16x4v a0 = __builtin_bit_cast(s16x4v, __builtin_amdgcn_ds_read_tr16_b64_v4i16((LAS s16x4v*)(vp + ks * 1024)));
;         const s16x4v a1 = __builtin_bit_cast(s16x4v, __builtin_amdgcn_ds_read_tr16_b64_v4i16((LAS s16x4v*)(vp + ks * 1024 + 512)));
;         const s16x4v b0 = __builtin_bit_cast(s16x4v, __builtin_amdgcn_ds_read_tr16_b64_v4i16((LAS s16x4v*)(vp + 4096 + ks * 1024)));
;         const s16x4v b1 = __builtin_bit_cast(s16x4v, __builtin_amdgcn_ds_read_tr16_b64_v4i16((LAS s16x4v*)(vp + 4096 + ks * 1024 + 512)));
;         const bf16x8v va = {a0[0], a0[1], a0[2], a0[3], a1[0], a1[1], a1[2], a1[3]}, vb = {b0[0], b0[1], b0[2], b0[3], b1[0], b1[1], b1[2], b1[3]};
;         const bf16x8v pa = __builtin_bit_cast(bf16x8v, pw[ks]);
;         o0 = __builtin_amdgcn_mfma_f32_32x32x16_bf16(pa, va, o0, 0, 0, 0); o1 = __builtin_amdgcn_mfma_f32_32x32x16_bf16(pa, vb, o1, 0, 0, 0); }
; }
; __device__ __forceinline__ void nsa_softmax_pv(NsaSm& st, f32x16& p0, f32x16& p1, const LAS unsigned char* vslot, LAS float* wsf, int lane, int r32, int hi, bool on = true) {
;     const float rmx = rowmax32(p0, p1); const float rm = on ? rmx : SNEG; const float mn = fmaxf(st.m, rm); const float f = __builtin_amdgcn_exp2f(st.m - mn); st.m = mn;
;     const float cs = on ? mn : 1.0e30f;
;     float s = 0.f;
; #pragma unroll
;     for (int r = 0; r < 16; ++r) { p0[r] = __builtin_amdgcn_exp2f(p0[r] - cs); p1[r] = __builtin_amdgcn_exp2f(p1[r] - cs); s += p0[r] + p1[r]; }
;     st.l = st.l * f + s;
.LBB0_1350:
	v_pk_add_f32 v[128:129], v[128:129], v[0:1] op_sel_hi:[1,0] neg_lo:[0,1] neg_hi:[0,1]
	v_pk_add_f32 v[130:131], v[130:131], v[0:1] op_sel_hi:[1,0] neg_lo:[0,1] neg_hi:[0,1]
	v_pk_add_f32 v[132:133], v[132:133], v[0:1] op_sel_hi:[1,0] neg_lo:[0,1] neg_hi:[0,1]
	v_pk_add_f32 v[134:135], v[134:135], v[0:1] op_sel_hi:[1,0] neg_lo:[0,1] neg_hi:[0,1]
	v_pk_add_f32 v[136:137], v[136:137], v[0:1] op_sel_hi:[1,0] neg_lo:[0,1] neg_hi:[0,1]
	v_pk_add_f32 v[138:139], v[138:139], v[0:1] op_sel_hi:[1,0] neg_lo:[0,1] neg_hi:[0,1]
	v_pk_add_f32 v[140:141], v[140:141], v[0:1] op_sel_hi:[1,0] neg_lo:[0,1] neg_hi:[0,1]
	v_pk_add_f32 v[142:143], v[142:143], v[0:1] op_sel_hi:[1,0] neg_lo:[0,1] neg_hi:[0,1]
	v_pk_add_f32 v[112:113], v[112:113], v[0:1] op_sel_hi:[1,0] neg_lo:[0,1] neg_hi:[0,1]
	v_pk_add_f32 v[114:115], v[114:115], v[0:1] op_sel_hi:[1,0] neg_lo:[0,1] neg_hi:[0,1]
	v_pk_add_f32 v[116:117], v[116:117], v[0:1] op_sel_hi:[1,0] neg_lo:[0,1] neg_hi:[0,1]
	v_pk_add_f32 v[118:119], v[118:119], v[0:1] op_sel_hi:[1,0] neg_lo:[0,1] neg_hi:[0,1]
	v_pk_add_f32 v[120:121], v[120:121], v[0:1] op_sel_hi:[1,0] neg_lo:[0,1] neg_hi:[0,1]
	v_pk_add_f32 v[122:123], v[122:123], v[0:1] op_sel_hi:[1,0] neg_lo:[0,1] neg_hi:[0,1]
	v_pk_add_f32 v[124:125], v[124:125], v[0:1] op_sel_hi:[1,0] neg_lo:[0,1] neg_hi:[0,1]
	v_pk_add_f32 v[126:127], v[126:127], v[0:1] op_sel_hi:[1,0] neg_lo:[0,1] neg_hi:[0,1]
	v_exp_f32_e32 v128, v128
	v_exp_f32_e32 v129, v129
	v_exp_f32_e32 v130, v130
	v_exp_f32_e32 v131, v131
	v_exp_f32_e32 v132, v132
	v_exp_f32_e32 v133, v133
	v_exp_f32_e32 v134, v134
	v_exp_f32_e32 v135, v135
	v_add_u32_e32 v3, s30, v238
	v_cvt_pk_bf16_f32 v4, v128, v129
	v_cvt_pk_bf16_f32 v5, v130, v131
	v_cvt_pk_bf16_f32 v6, v132, v133
	v_cvt_pk_bf16_f32 v7, v134, v135
	ds_read_b64_tr_b16 v[8:9], v3 offset:17408
	ds_read_b64_tr_b16 v[10:11], v3 offset:17920
	v_exp_f32_e32 v136, v136
	v_exp_f32_e32 v137, v137
	v_exp_f32_e32 v138, v138
	v_exp_f32_e32 v139, v139
	v_exp_f32_e32 v140, v140
	v_exp_f32_e32 v141, v141
	v_exp_f32_e32 v142, v142
	s_waitcnt lgkmcnt(0)
	v_mfma_f32_32x32x16_bf16 v[96:111], v[4:7], v[8:11], v[96:111]
	ds_read_b64_tr_b16 v[8:9], v3 offset:18432
	ds_read_b64_tr_b16 v[144:145], v3 offset:21504
	ds_read_b64_tr_b16 v[146:147], v3 offset:22016
	ds_read_b64_tr_b16 v[10:11], v3 offset:18944
	v_exp_f32_e32 v143, v143
	v_cvt_pk_bf16_f32 v12, v136, v137
	v_cvt_pk_bf16_f32 v13, v138, v139
	v_cvt_pk_bf16_f32 v14, v140, v141
	v_cvt_pk_bf16_f32 v15, v142, v143
	v_exp_f32_e32 v112, v112
	s_waitcnt lgkmcnt(1)
	v_mfma_f32_32x32x16_bf16 v[80:95], v[4:7], v[144:147], v[80:95]
	ds_read_b64_tr_b16 v[4:5], v3 offset:22528
	ds_read_b64_tr_b16 v[6:7], v3 offset:23040
	v_exp_f32_e32 v113, v113
	v_exp_f32_e32 v114, v114
	v_exp_f32_e32 v115, v115
	v_exp_f32_e32 v116, v116
	v_exp_f32_e32 v117, v117
	v_exp_f32_e32 v118, v118
	v_exp_f32_e32 v119, v119
	s_waitcnt lgkmcnt(2)
	v_mfma_f32_32x32x16_bf16 v[96:111], v[12:15], v[8:11], v[96:111]
	v_cvt_pk_bf16_f32 v8, v112, v113
	v_cvt_pk_bf16_f32 v9, v114, v115
	v_cvt_pk_bf16_f32 v10, v116, v117
	v_cvt_pk_bf16_f32 v11, v118, v119
	s_waitcnt lgkmcnt(0)
	v_mfma_f32_32x32x16_bf16 v[80:95], v[12:15], v[4:7], v[80:95]
	ds_read_b64_tr_b16 v[4:5], v3 offset:19456
	ds_read_b64_tr_b16 v[6:7], v3 offset:19968
	v_exp_f32_e32 v120, v120
	v_exp_f32_e32 v121, v121
	v_exp_f32_e32 v122, v122
	v_exp_f32_e32 v123, v123
	v_exp_f32_e32 v124, v124
	v_exp_f32_e32 v125, v125
	v_exp_f32_e32 v126, v126
	v_exp_f32_e32 v127, v127
	s_waitcnt lgkmcnt(0)
	v_mfma_f32_32x32x16_bf16 v[96:111], v[8:11], v[4:7], v[96:111]
	ds_read_b64_tr_b16 v[4:5], v3 offset:20480
	ds_read_b64_tr_b16 v[12:13], v3 offset:23552
	ds_read_b64_tr_b16 v[14:15], v3 offset:24064
	ds_read_b64_tr_b16 v[6:7], v3 offset:20992
	v_cvt_pk_bf16_f32 v144, v120, v121
	v_cvt_pk_bf16_f32 v145, v122, v123
	v_cvt_pk_bf16_f32 v146, v124, v125
	v_cvt_pk_bf16_f32 v147, v126, v127
	s_andn2_b64 vcc, exec, s[16:17]
	s_waitcnt lgkmcnt(1)
	v_mfma_f32_32x32x16_bf16 v[80:95], v[8:11], v[12:15], v[80:95]
	s_waitcnt lgkmcnt(0)
	v_mfma_f32_32x32x16_bf16 v[96:111], v[144:147], v[4:7], v[96:111]
	ds_read_b64_tr_b16 v[4:5], v3 offset:24576
	ds_read_b64_tr_b16 v[6:7], v3 offset:25088
	s_waitcnt lgkmcnt(0)
	v_mfma_f32_32x32x16_bf16 v[80:95], v[144:147], v[4:7], v[80:95]
	s_cbranch_vccnz .LBB0_1352
	s_xor_b32 s8, s30, 0x2000
	v_add_u32_e32 v3, s8, v251
	s_waitcnt vmcnt(1)
	ds_write_b128 v3, v[224:227] offset:1024
	s_waitcnt vmcnt(0)
	ds_write_b128 v3, v[228:231] offset:17408
.LBB0_1352:
	v_pk_add_f32 v[128:129], v[128:129], v[130:131]
	v_pk_add_f32 v[132:133], v[132:133], v[134:135]
	v_pk_add_f32 v[136:137], v[136:137], v[138:139]
	v_pk_add_f32 v[140:141], v[140:141], v[142:143]
	v_pk_add_f32 v[112:113], v[112:113], v[114:115]
	v_pk_add_f32 v[116:117], v[116:117], v[118:119]
	v_pk_add_f32 v[120:121], v[120:121], v[122:123]
	v_pk_add_f32 v[124:125], v[124:125], v[126:127]
	v_pk_add_f32 v[128:129], v[128:129], v[132:133]
	v_pk_add_f32 v[136:137], v[136:137], v[140:141]
	v_pk_add_f32 v[112:113], v[112:113], v[116:117]
	v_pk_add_f32 v[120:121], v[120:121], v[124:125]
	v_pk_add_f32 v[128:129], v[128:129], v[136:137]
	v_pk_add_f32 v[112:113], v[112:113], v[120:121]
	v_pk_add_f32 v[128:129], v[128:129], v[112:113]
	v_add_f32_e32 v3, v128, v129
	s_xor_b32 s25, s25, 1
	s_add_i32 s13, s13, -1
	s_add_i32 s24, s24, 64
	v_fmac_f32_e32 v3, v250, v2
	s_cmp_gt_i32 s19, s20
	s_waitcnt lgkmcnt(0)
	s_barrier
	s_cbranch_scc0 .LBB0_1354
	v_mov_b32_e32 v250, v3
	v_mov_b32_e32 v233, v0
	s_branch .LBB0_1340
